# DIFF sub-item prologue: bias-table byte lookup and its dependent load overlap the Q/K/V tile loads instead of two full waits in front of them
# speedup vs baseline: 1.0114x; 1.0014x over previous
; template <int MODE>
; __device__ __forceinline__ void attn_item(const Params& P, int layer, int b, int h, int map, int qb) {
;     ...
;   if (MODE != 0) { if (tid < 129) tab[tid] = P.rel_bias[T5B[tid] * 10 + bcol] * LOG2E; }
.LBB0_1240:
	s_mov_b64 s[2:3], -1
	s_and_b64 vcc, exec, s[8:9]
	s_cbranch_vccz .LBB0_1287
	v_mov_b32_e32 v2, v155
	s_nop 0
	v_readfirstlane_b32 s4, v2
	v_cmp_gt_i32_e32 vcc, s33, v2
	s_and_saveexec_b64 s[2:3], vcc
	s_cbranch_execz .LBB0_1243
	v_ashrrev_i32_e32 v3, 31, v2
	s_getpc_b64 s[24:25]
	s_add_u32 s24, s24, _ZL3T5B@rel32@lo+4
	s_addc_u32 s25, s25, _ZL3T5B@rel32@hi+12
	v_lshl_add_u64 v[4:5], s[24:25], 0, v[2:3]
	s_waitcnt lgkmcnt(0)
	global_load_ubyte v122, v[4:5], off
	v_readlane_b32 s12, v253, 24
	v_readlane_b32 s16, v253, 28
	v_readlane_b32 s17, v253, 29
	v_readlane_b32 s13, v253, 25
	v_readlane_b32 s14, v253, 26
	v_readlane_b32 s15, v253, 27
	v_readlane_b32 s18, v253, 30
	v_readlane_b32 s19, v253, 31
	v_readlane_b32 s20, v253, 32
	v_readlane_b32 s21, v253, 33
	v_readlane_b32 s22, v253, 34
	v_readlane_b32 s23, v253, 35
	v_readlane_b32 s24, v253, 36
	v_readlane_b32 s25, v253, 37
	v_readlane_b32 s26, v253, 38
	v_readlane_b32 s27, v253, 39

; template <int MODE>
; __device__ __forceinline__ void attn_item(const Params& P, int layer, int b, int h, int map, int qb) {
;     ...
;   if (MODE != 0) { if (tid < 129) tab[tid] = P.rel_bias[T5B[tid] * 10 + bcol] * LOG2E; }
;   bf16x8 qf[NST];
; #pragma unroll
;   for (int s = 0; s < NST; ++s) qf[s] = qvalid ? *(const bf16x8*)(qp + (size_t)e_q * KLD + s * 16 + hh * 8) : (bf16x8){0, 0, 0, 0, 0, 0, 0, 0};
;   int tstart = 1, ntl;
;   if (meta) ntl = 1; else if (MODE == 2) { tstart = max(1, 4 * qb - 1); ntl = 4 * qb + 6 - tstart; } else ntl = 4 * qb + 5;
;   SM sa;
;   sa.m = NEG; sa.l = 0.f;
; #pragma unroll
;   for (int i = 0; i < 16; ++i) { sa.o0[i] = 0.f; sa.o1[i] = 0.f; }
;   if (MODE == 2) { sa.m = P.sinks[layer * 6 + h] * LOG2E; sa.l = hh == 0 ? 1.f : 0.f; }
;   float cfar = 0.f; if (MODE == 1) cfar = P.rel_bias[31 * 10 + bcol] * LOG2E;
;   struct Stage { u32x4 k[NLK], v; };
;   Stage stX, stY;
;   auto issue = [&](Stage& st, int t) {
; #pragma unroll
;     for (int u = 0; u < NLK; ++u) { int c = tid + 512 * u; if (c >= NKC) c -= (NKC % 512 == 0 ? 512 : NKC % 512);
;       const int row = c / CPR, cc = c % CPR; st.k[u] = *(const u32x4*)(kp + (size_t)(64 * t + row) * KLD + cc * 8); }
;     { const int row = tid >> 3, cc = tid & 7; st.v = *(const u32x4*)(vp + (size_t)row * E + 64 * t + cc * 8); }
;   };
;   auto commit = [&](const Stage& st, int bufi) {
; #pragma unroll
;     for (int u = 0; u < NLK; ++u) { int c = tid + 512 * u; if (c >= NKC) c -= (NKC % 512 == 0 ? 512 : NKC % 512);
;       const int row = c / CPR, cc = c % CPR; *(LAS u32x4*)(lds + bufi * KBUF + row * KSTR + cc * 16) = st.k[u]; }
;     { const int row = tid >> 3, cc = tid & 7; *(LAS u32x4*)(lds + 4 * KBUF + bufi * VBUF + row * 144 + cc * 16) = st.v; }
;   };
;   auto tile_of = [&](int i) { return i == 0 ? 0 : tstart + i - 1; };
;   auto skipf = [&](int t) { bool sk = !active; if (t > 0) { if (64 * t > eq0 + 31) sk = true; if (MODE == 2 && eq0 - (64 * t + 63) >= 128) sk = true; } return sk; };
;   const int pr = (r & 0x13) | ((r & 4) << 1) | ((r & 8) >> 1);
;   auto lookf = [&](int t) { return MODE != 0 && (t == 0 || MODE == 2 || (eq0 - (64 * t + 63) < 128)); };
;   auto qk = [&](f32x16& s0, f32x16& s1, float& boff, int bufi, int t) {
;     const ldsp_t kbuf = lds + bufi * KBUF;
;     __builtin_amdgcn_s_setprio(1);
;     boff = sa.m > -1e29f ? sa.m : 0.f;
.LBB0_1247:
	s_or_b64 exec, exec, s[2:3]
	v_cmp_lt_i32_e32 vcc, 63, v166
	v_subrev_u32_e32 v4, 48, v166
	v_lshlrev_b32_e32 v168, 3, v6
	v_cndmask_b32_e32 v169, v166, v4, vcc
	global_load_dword v4, v1, s[38:39] offset:1240
	v_lshlrev_b32_e32 v5, 1, v2
	v_lshrrev_b32_e32 v6, 1, v2
	v_and_b32_e32 v5, 8, v5
	v_and_b32_e32 v6, 4, v6
	v_cmp_lt_i32_e32 vcc, s92, v2
	s_lshl_b32 s2, s37, 1
	s_add_u32 s2, s61, s2
	s_addc_u32 s3, s58, 0
	v_and_b32_e32 v167, 63, v2
	v_ashrrev_i32_e32 v28, 3, v2
	v_mov_b64_e32 v[8:9], s[34:35]
	s_or_b64 s[68:69], s[72:73], s[4:5]
	v_mad_i64_i32 v[22:23], s[4:5], v28, s95, v[8:9]
	v_mov_b32_e32 v25, v1
	s_lshl_b32 s90, s76, 1
	v_lshl_add_u64 v[16:17], v[22:23], 0, s[90:91]
	s_lshl_b32 s90, s77, 1
	v_mul_u32_u24_e32 v224, 0x90, v3
	v_mov_b32_e32 v3, v1
	v_mov_b32_e32 v223, 0xf149f2ca
	s_xor_b64 s[40:41], s[68:69], -1
	s_or_b32 s37, s36, 31
	s_sub_i32 s80, s36, 63
	v_add_u32_e32 v225, 48, v169
	v_add_u32_e32 v226, s51, v169
	s_mov_b32 s48, 0
	v_mov_b32_e32 v177, 0xf149f2ca
	v_mov_b32_e32 v228, 0
	s_waitcnt vmcnt(0)
	v_cmp_gt_i32_e64 s[98:99], s33, v155
	s_and_saveexec_b64 s[6:7], s[98:99]
	v_mad_u32_u24 v122, v122, 10, s64
	v_mov_b32_e32 v123, 0
	v_readlane_b32 s18, v253, 28
	v_readlane_b32 s19, v253, 29
	s_nop 3
	v_lshl_add_u64 v[124:125], v[122:123], 2, s[18:19]
	global_load_dword v122, v[124:125], off
	s_or_b64 exec, exec, s[6:7]
	v_mul_f32_e32 v221, 0x3fb8aa3b, v4
	v_and_b32_e32 v4, 19, v2
	v_or3_b32 v26, v4, v5, v6
	v_add_u32_e32 v4, 0xffffff00, v2
	v_cndmask_b32_e32 v4, v2, v4, vcc
	v_ashrrev_i32_e32 v5, 31, v4
	v_lshrrev_b32_e32 v5, 30, v5
	v_add_u32_e32 v5, v4, v5
	v_ashrrev_i32_e32 v170, 2, v5
	v_and_b32_e32 v5, -4, v5
	v_sub_u32_e32 v27, v4, v5
	v_ashrrev_i32_e32 v171, 31, v170
	v_lshlrev_b32_e32 v6, 3, v27
	v_lshlrev_b64 v[4:5], 7, v[170:171]
	v_ashrrev_i32_e32 v7, 31, v6
	v_lshl_add_u64 v[4:5], s[2:3], 0, v[4:5]
	v_lshlrev_b64 v[20:21], 1, v[6:7]
	v_lshl_add_u64 v[4:5], v[4:5], 0, v[20:21]
	global_load_dwordx4 v[4:7], v[4:5], off
	v_add_u32_e32 v12, s76, v170
	v_lshlrev_b32_e32 v2, 4, v2
	v_ashrrev_i32_e32 v13, 31, v12
	v_and_b32_e32 v24, 0x70, v2
	v_lshlrev_b64 v[12:13], 7, v[12:13]
	v_lshl_add_u64 v[172:173], v[22:23], 0, v[24:25]
	v_lshl_add_u64 v[12:13], s[2:3], 0, v[12:13]
	global_load_dwordx4 v[8:11], v[172:173], off
	v_lshl_add_u64 v[12:13], v[12:13], 0, v[20:21]
	global_load_dwordx4 v[12:15], v[12:13], off
	v_lshl_add_u64 v[16:17], v[16:17], 0, v[24:25]
	global_load_dwordx4 v[16:19], v[16:17], off
	v_mul_lo_u32 v2, v170, s86
	v_lshlrev_b32_e32 v27, 4, v27
	v_add3_u32 v171, 0, v2, v27
	v_mul_lo_u32 v2, v28, s54
	v_add3_u32 v222, 0, v2, v24
	v_mul_u32_u24_e32 v2, 0x50, v26
	v_lshl_add_u64 v[174:175], s[2:3], 0, v[20:21]
	v_add3_u32 v227, 0, v2, v0
	v_mov_b32_e32 v2, v1
	s_waitcnt vmcnt(3)
	ds_write_b128 v171, v[4:7]
	v_add_u32_e32 v4, s77, v170
	v_ashrrev_i32_e32 v5, 31, v4
	v_lshlrev_b64 v[4:5], 7, v[4:5]
	v_lshl_add_u64 v[4:5], s[2:3], 0, v[4:5]
	s_waitcnt vmcnt(2)
	ds_write_b128 v222, v[8:11] offset:20480
	s_waitcnt vmcnt(1)
	ds_write_b128 v171, v[12:15] offset:5120
	s_waitcnt vmcnt(0)
	ds_write_b128 v222, v[16:19] offset:29696
	v_lshl_add_u64 v[4:5], v[4:5], 0, v[20:21]
	global_load_dwordx4 v[106:109], v[4:5], off
	v_lshl_add_u64 v[4:5], v[22:23], 0, s[90:91]
	v_lshl_add_u64 v[4:5], v[4:5], 0, v[24:25]
	global_load_dwordx4 v[110:113], v[4:5], off
	v_add_u32_e32 v4, s50, v170
	v_ashrrev_i32_e32 v5, 31, v4
	v_lshlrev_b64 v[4:5], 7, v[4:5]
	v_lshl_add_u64 v[4:5], s[2:3], 0, v[4:5]
	v_lshl_add_u64 v[4:5], v[4:5], 0, v[20:21]
	s_lshl_b32 s90, s50, 1
	global_load_dwordx4 v[114:117], v[4:5], off
	v_lshl_add_u64 v[4:5], v[22:23], 0, s[90:91]
	v_lshl_add_u64 v[4:5], v[4:5], 0, v[24:25]
	global_load_dwordx4 v[118:121], v[4:5], off
	v_mov_b32_e32 v16, v1
	v_mov_b32_e32 v17, v1
	v_mov_b32_e32 v4, v1
	v_mov_b32_e32 v5, v1
	v_mov_b32_e32 v6, v1
	v_mov_b32_e32 v7, v1
	v_mov_b32_e32 v8, v1
	v_mov_b32_e32 v9, v1
	v_mov_b32_e32 v10, v1
	v_mov_b32_e32 v11, v1
	v_mov_b32_e32 v12, v1
	v_mov_b32_e32 v13, v1
	v_mov_b32_e32 v14, v1
	v_mov_b32_e32 v15, v1
	v_mov_b64_e32 v[32:33], v[16:17]
	v_mov_b64_e32 v[30:31], v[14:15]
	v_mov_b64_e32 v[28:29], v[12:13]
	v_mov_b64_e32 v[26:27], v[10:11]
	v_mov_b64_e32 v[24:25], v[8:9]
	v_mov_b64_e32 v[22:23], v[6:7]
	v_mov_b64_e32 v[20:21], v[4:5]
	v_mov_b64_e32 v[18:19], v[2:3]
	v_cmp_gt_i32_e64 s[98:99], s33, v155
	s_and_saveexec_b64 s[6:7], s[98:99]
	s_waitcnt vmcnt(4)
	v_mul_f32_e32 v122, 0x3fb8aa3b, v122
	v_lshlrev_b32_e32 v123, 2, v155
	ds_write_b32 v123, v122 offset:57344
	s_or_b64 exec, exec, s[6:7]
	s_waitcnt lgkmcnt(0)
	s_barrier
	s_branch .LBB0_1251
